# out_rows: the six per-head wave_sum butterflies of a row issued together (6 LDS round trips per row instead of 18), silu math fills the waits
# speedup vs baseline: 1.0079x; 1.0079x over previous
.LBB0_1908:
	s_add_i32 s4, s8, s34
	s_cmpk_lt_i32 s4, 0x4000
	s_cselect_b32 s0, s4, s8
	s_mul_hi_i32 s1, s0, 0x1c00
	s_mulk_i32 s0, 0x1c00
	s_add_u32 s12, s10, s0
	s_addc_u32 s13, s11, s1
	s_ashr_i32 s9, s8, 31
	s_mul_i32 s0, s8, 0x1c00
	v_lshl_add_u64 v[4:5], s[12:13], 0, v[160:161]
	s_mov_b64 s[14:15], 0x1200
	s_mul_hi_i32 s1, s8, 0x1c00
	s_add_u32 s0, s10, s0
	v_lshl_add_u64 v[6:7], v[4:5], 0, s[14:15]
	v_add_co_u32_e32 v4, vcc, s22, v4
	s_addc_u32 s1, s11, s1
	s_nop 0
	v_addc_co_u32_e32 v5, vcc, 0, v5, vcc
	global_load_dword v35, v160, s[12:13]
	global_load_dword v33, v[4:5], off offset:512
	global_load_dword v34, v160, s[12:13] offset:256
	global_load_dword v32, v[6:7], off offset:256
	global_load_dword v31, v160, s[12:13] offset:512
	global_load_dword v29, v[6:7], off offset:512
	global_load_dword v30, v160, s[12:13] offset:768
	global_load_dword v28, v[6:7], off offset:768
	global_load_dword v27, v160, s[12:13] offset:1024
	global_load_dword v25, v[6:7], off offset:1024
	global_load_dword v26, v160, s[12:13] offset:1280
	global_load_dword v24, v[6:7], off offset:1280
	v_lshl_add_u64 v[4:5], s[0:1], 0, v[160:161]
	v_lshl_add_u64 v[6:7], v[4:5], 0, s[14:15]
	v_add_co_u32_e32 v4, vcc, s22, v4
	global_load_dword v36, v[6:7], off offset:1280
	global_load_dword v37, v160, s[0:1] offset:1280
	global_load_dword v38, v[6:7], off offset:1024
	global_load_dword v39, v160, s[0:1] offset:1024
	global_load_dword v40, v[6:7], off offset:768
	global_load_dword v41, v160, s[0:1] offset:768
	global_load_dword v42, v[6:7], off offset:512
	global_load_dword v43, v160, s[0:1] offset:512
	global_load_dword v44, v[6:7], off offset:256
	global_load_dword v11, v160, s[0:1] offset:256
	v_addc_co_u32_e32 v5, vcc, 0, v5, vcc
	global_load_dword v7, v[4:5], off offset:512
	global_load_dword v6, v160, s[0:1]
	s_lshl_b64 s[8:9], s[8:9], 11
	s_mov_b32 s0, 0x358637bd
	v_lshl_add_u64 v[4:5], v[2:3], 0, s[8:9]
	s_brev_b32 s8, 60
	s_cmpk_gt_i32 s4, 0x3fff
	s_waitcnt vmcnt(0)
	v_lshlrev_b32_e32 v46, 16, v6
	v_and_b32_e32 v47, 0xffff0000, v6
	v_lshlrev_b32_e32 v48, 16, v11
	v_and_b32_e32 v49, 0xffff0000, v11
	v_lshlrev_b32_e32 v50, 16, v43
	v_and_b32_e32 v51, 0xffff0000, v43
	v_lshlrev_b32_e32 v52, 16, v41
	v_and_b32_e32 v53, 0xffff0000, v41
	v_lshlrev_b32_e32 v54, 16, v39
	v_and_b32_e32 v55, 0xffff0000, v39
	v_lshlrev_b32_e32 v56, 16, v37
	v_and_b32_e32 v57, 0xffff0000, v37
	v_lshlrev_b32_e32 v58, 16, v7
	v_and_b32_e32 v59, 0xffff0000, v7
	v_lshlrev_b32_e32 v60, 16, v44
	v_and_b32_e32 v61, 0xffff0000, v44
	v_lshlrev_b32_e32 v62, 16, v42
	v_and_b32_e32 v63, 0xffff0000, v42
	v_lshlrev_b32_e32 v64, 16, v40
	v_and_b32_e32 v65, 0xffff0000, v40
	v_lshlrev_b32_e32 v66, 16, v38
	v_and_b32_e32 v67, 0xffff0000, v38
	v_lshlrev_b32_e32 v68, 16, v36
	v_and_b32_e32 v69, 0xffff0000, v36
	v_pk_mul_f32 v[82:83], v[46:47], v[46:47]
	v_pk_mul_f32 v[84:85], v[48:49], v[48:49]
	v_pk_mul_f32 v[86:87], v[50:51], v[50:51]
	v_pk_mul_f32 v[88:89], v[52:53], v[52:53]
	v_pk_mul_f32 v[90:91], v[54:55], v[54:55]
	v_pk_mul_f32 v[92:93], v[56:57], v[56:57]
	v_add_f32_e32 v94, v82, v83
	v_add_f32_e32 v95, v84, v85
	v_add_f32_e32 v96, v86, v87
	v_add_f32_e32 v97, v88, v89
	v_add_f32_e32 v98, v90, v91
	v_add_f32_e32 v99, v92, v93
	ds_bpermute_b32 v100, v18, v94
	ds_bpermute_b32 v101, v18, v95
	ds_bpermute_b32 v102, v18, v96
	ds_bpermute_b32 v103, v18, v97
	ds_bpermute_b32 v104, v18, v98
	ds_bpermute_b32 v105, v18, v99
	v_mul_f32_e32 v70, 0xbfb8aa3b, v58
	v_mul_f32_e32 v71, 0xbfb8aa3b, v59
	v_mul_f32_e32 v72, 0xbfb8aa3b, v60
	v_mul_f32_e32 v73, 0xbfb8aa3b, v61
	v_mul_f32_e32 v74, 0xbfb8aa3b, v62
	v_mul_f32_e32 v75, 0xbfb8aa3b, v63
	v_mul_f32_e32 v76, 0xbfb8aa3b, v64
	v_mul_f32_e32 v77, 0xbfb8aa3b, v65
	v_mul_f32_e32 v78, 0xbfb8aa3b, v66
	v_mul_f32_e32 v79, 0xbfb8aa3b, v67
	v_mul_f32_e32 v80, 0xbfb8aa3b, v68
	v_mul_f32_e32 v81, 0xbfb8aa3b, v69
	s_waitcnt lgkmcnt(0)
	v_pk_add_f32 v[94:95], v[94:95], v[100:101]
	v_pk_add_f32 v[96:97], v[96:97], v[102:103]
	v_pk_add_f32 v[98:99], v[98:99], v[104:105]
	ds_bpermute_b32 v100, v19, v94
	ds_bpermute_b32 v101, v19, v95
	ds_bpermute_b32 v102, v19, v96
	ds_bpermute_b32 v103, v19, v97
	ds_bpermute_b32 v104, v19, v98
	ds_bpermute_b32 v105, v19, v99
	v_exp_f32_e32 v70, v70
	v_exp_f32_e32 v71, v71
	v_exp_f32_e32 v72, v72
	v_exp_f32_e32 v73, v73
	v_exp_f32_e32 v74, v74
	v_exp_f32_e32 v75, v75
	v_exp_f32_e32 v76, v76
	v_exp_f32_e32 v77, v77
	v_exp_f32_e32 v78, v78
	v_exp_f32_e32 v79, v79
	v_exp_f32_e32 v80, v80
	v_exp_f32_e32 v81, v81
	s_waitcnt lgkmcnt(0)
	v_pk_add_f32 v[94:95], v[94:95], v[100:101]
	v_pk_add_f32 v[96:97], v[96:97], v[102:103]
	v_pk_add_f32 v[98:99], v[98:99], v[104:105]
	ds_bpermute_b32 v100, v20, v94
	ds_bpermute_b32 v101, v20, v95
	ds_bpermute_b32 v102, v20, v96
	ds_bpermute_b32 v103, v20, v97
	ds_bpermute_b32 v104, v20, v98
	ds_bpermute_b32 v105, v20, v99
	v_add_f32_e32 v70, 1.0, v70
	v_add_f32_e32 v71, 1.0, v71
	v_add_f32_e32 v72, 1.0, v72
	v_add_f32_e32 v73, 1.0, v73
	v_add_f32_e32 v74, 1.0, v74
	v_add_f32_e32 v75, 1.0, v75
	v_add_f32_e32 v76, 1.0, v76
	v_add_f32_e32 v77, 1.0, v77
	v_add_f32_e32 v78, 1.0, v78
	v_add_f32_e32 v79, 1.0, v79
	v_add_f32_e32 v80, 1.0, v80
	v_add_f32_e32 v81, 1.0, v81
	s_waitcnt lgkmcnt(0)
	v_pk_add_f32 v[94:95], v[94:95], v[100:101]
	v_pk_add_f32 v[96:97], v[96:97], v[102:103]
	v_pk_add_f32 v[98:99], v[98:99], v[104:105]
	ds_bpermute_b32 v100, v21, v94
	ds_bpermute_b32 v101, v21, v95
	ds_bpermute_b32 v102, v21, v96
	ds_bpermute_b32 v103, v21, v97
	ds_bpermute_b32 v104, v21, v98
	ds_bpermute_b32 v105, v21, v99
	v_rcp_f32_e32 v70, v70
	v_rcp_f32_e32 v71, v71
	v_rcp_f32_e32 v72, v72
	v_rcp_f32_e32 v73, v73
	v_rcp_f32_e32 v74, v74
	v_rcp_f32_e32 v75, v75
	v_rcp_f32_e32 v76, v76
	v_rcp_f32_e32 v77, v77
	v_rcp_f32_e32 v78, v78
	v_rcp_f32_e32 v79, v79
	v_rcp_f32_e32 v80, v80
	v_rcp_f32_e32 v81, v81
	s_waitcnt lgkmcnt(0)
	v_pk_add_f32 v[94:95], v[94:95], v[100:101]
	v_pk_add_f32 v[96:97], v[96:97], v[102:103]
	v_pk_add_f32 v[98:99], v[98:99], v[104:105]
	ds_bpermute_b32 v100, v22, v94
	ds_bpermute_b32 v101, v22, v95
	ds_bpermute_b32 v102, v22, v96
	ds_bpermute_b32 v103, v22, v97
	ds_bpermute_b32 v104, v22, v98
	ds_bpermute_b32 v105, v22, v99
	v_pk_mul_f32 v[58:59], v[70:71], v[58:59]
	v_pk_mul_f32 v[60:61], v[72:73], v[60:61]
	v_pk_mul_f32 v[62:63], v[74:75], v[62:63]
	v_pk_mul_f32 v[64:65], v[76:77], v[64:65]
	v_pk_mul_f32 v[66:67], v[78:79], v[66:67]
	v_pk_mul_f32 v[68:69], v[80:81], v[68:69]
	v_mov_b32_e32 v106, 0x358637bd
	s_waitcnt lgkmcnt(0)
	v_pk_add_f32 v[94:95], v[94:95], v[100:101]
	v_pk_add_f32 v[96:97], v[96:97], v[102:103]
	v_pk_add_f32 v[98:99], v[98:99], v[104:105]
	ds_bpermute_b32 v100, v23, v94
	ds_bpermute_b32 v101, v23, v95
	ds_bpermute_b32 v102, v23, v96
	ds_bpermute_b32 v103, v23, v97
	ds_bpermute_b32 v104, v23, v98
	ds_bpermute_b32 v105, v23, v99
	s_waitcnt lgkmcnt(0)
	v_pk_add_f32 v[94:95], v[94:95], v[100:101]
	v_pk_add_f32 v[96:97], v[96:97], v[102:103]
	v_pk_add_f32 v[98:99], v[98:99], v[104:105]
	s_nop 0
	v_fma_f32 v94, v94, s8, v106
	v_fma_f32 v95, v95, s8, v106
	v_fma_f32 v96, v96, s8, v106
	v_fma_f32 v97, v97, s8, v106
	v_fma_f32 v98, v98, s8, v106
	v_fma_f32 v99, v99, s8, v106
	v_mul_f32_e32 v108, 0x4b800000, v94
	v_mul_f32_e32 v109, 0x4b800000, v95
	v_cmp_gt_f32_e32 vcc, s26, v94
	v_cmp_gt_f32_e64 s[0:1], s26, v95
	s_nop 0
	v_cndmask_b32_e32 v94, v94, v108, vcc
	v_cndmask_b32_e64 v95, v95, v109, s[0:1]
	v_rsq_f32_e32 v94, v94
	v_rsq_f32_e32 v95, v95
	v_mul_f32_e32 v108, 0x45800000, v94
	v_mul_f32_e32 v109, 0x45800000, v95
	v_cndmask_b32_e32 v114, v94, v108, vcc
	v_cndmask_b32_e64 v116, v95, v109, s[0:1]
	v_mul_f32_e32 v110, 0x4b800000, v96
	v_mul_f32_e32 v111, 0x4b800000, v97
	v_cmp_gt_f32_e32 vcc, s26, v96
	v_cmp_gt_f32_e64 s[0:1], s26, v97
	s_nop 0
	v_cndmask_b32_e32 v96, v96, v110, vcc
	v_cndmask_b32_e64 v97, v97, v111, s[0:1]
	v_rsq_f32_e32 v96, v96
	v_rsq_f32_e32 v97, v97
	v_mul_f32_e32 v110, 0x45800000, v96
	v_mul_f32_e32 v111, 0x45800000, v97
	v_cndmask_b32_e32 v118, v96, v110, vcc
	v_cndmask_b32_e64 v120, v97, v111, s[0:1]
	v_mul_f32_e32 v112, 0x4b800000, v98
	v_mul_f32_e32 v113, 0x4b800000, v99
	v_cmp_gt_f32_e32 vcc, s26, v98
	v_cmp_gt_f32_e64 s[0:1], s26, v99
	s_nop 0
	v_cndmask_b32_e32 v98, v98, v112, vcc
	v_cndmask_b32_e64 v99, v99, v113, s[0:1]
	v_rsq_f32_e32 v98, v98
	v_rsq_f32_e32 v99, v99
	v_mul_f32_e32 v112, 0x45800000, v98
	v_mul_f32_e32 v113, 0x45800000, v99
	v_cndmask_b32_e32 v122, v98, v112, vcc
	v_cndmask_b32_e64 v124, v99, v113, s[0:1]
	v_pk_mul_f32 v[46:47], v[114:115], v[46:47] op_sel_hi:[0,1]
	v_pk_mul_f32 v[48:49], v[116:117], v[48:49] op_sel_hi:[0,1]
	v_pk_mul_f32 v[50:51], v[118:119], v[50:51] op_sel_hi:[0,1]
	v_pk_mul_f32 v[52:53], v[120:121], v[52:53] op_sel_hi:[0,1]
	v_pk_mul_f32 v[54:55], v[122:123], v[54:55] op_sel_hi:[0,1]
	v_pk_mul_f32 v[56:57], v[124:125], v[56:57] op_sel_hi:[0,1]
	v_pk_mul_f32 v[46:47], v[0:1], v[46:47]
	v_pk_mul_f32 v[48:49], v[0:1], v[48:49]
	v_pk_mul_f32 v[50:51], v[0:1], v[50:51]
	v_pk_mul_f32 v[52:53], v[0:1], v[52:53]
	v_pk_mul_f32 v[54:55], v[0:1], v[54:55]
	v_pk_mul_f32 v[56:57], v[0:1], v[56:57]
	v_pk_mul_f32 v[46:47], v[58:59], v[46:47]
	v_pk_mul_f32 v[48:49], v[60:61], v[48:49]
	v_pk_mul_f32 v[50:51], v[62:63], v[50:51]
	v_pk_mul_f32 v[52:53], v[64:65], v[52:53]
	v_pk_mul_f32 v[54:55], v[66:67], v[54:55]
	v_pk_mul_f32 v[56:57], v[68:69], v[56:57]
	v_cvt_pk_bf16_f32 v108, v46, v47
	v_cvt_pk_bf16_f32 v109, v48, v49
	v_cvt_pk_bf16_f32 v110, v50, v51
	v_cvt_pk_bf16_f32 v111, v52, v53
	v_cvt_pk_bf16_f32 v112, v54, v55
	v_cvt_pk_bf16_f32 v113, v56, v57
	global_store_dword v[4:5], v108, off
	global_store_dword v[4:5], v109, off offset:256
	global_store_dword v[4:5], v110, off offset:512
	global_store_dword v[4:5], v111, off offset:768
	global_store_dword v[4:5], v112, off offset:1024
	global_store_dword v[4:5], v113, off offset:1280
	s_cbranch_scc1 .LBB0_1907
	s_ashr_i32 s5, s4, 31
	s_lshl_b64 s[0:1], s[4:5], 11
	v_lshl_add_u64 v[4:5], v[2:3], 0, s[0:1]
	v_lshlrev_b32_e32 v46, 16, v35
	v_and_b32_e32 v47, 0xffff0000, v35
	v_lshlrev_b32_e32 v48, 16, v34
	v_and_b32_e32 v49, 0xffff0000, v34
	v_lshlrev_b32_e32 v50, 16, v31
	v_and_b32_e32 v51, 0xffff0000, v31
	v_lshlrev_b32_e32 v52, 16, v30
	v_and_b32_e32 v53, 0xffff0000, v30
	v_lshlrev_b32_e32 v54, 16, v27
	v_and_b32_e32 v55, 0xffff0000, v27
	v_lshlrev_b32_e32 v56, 16, v26
	v_and_b32_e32 v57, 0xffff0000, v26
	v_lshlrev_b32_e32 v58, 16, v33
	v_and_b32_e32 v59, 0xffff0000, v33
	v_lshlrev_b32_e32 v60, 16, v32
	v_and_b32_e32 v61, 0xffff0000, v32
	v_lshlrev_b32_e32 v62, 16, v29
	v_and_b32_e32 v63, 0xffff0000, v29
	v_lshlrev_b32_e32 v64, 16, v28
	v_and_b32_e32 v65, 0xffff0000, v28
	v_lshlrev_b32_e32 v66, 16, v25
	v_and_b32_e32 v67, 0xffff0000, v25
	v_lshlrev_b32_e32 v68, 16, v24
	v_and_b32_e32 v69, 0xffff0000, v24
	v_pk_mul_f32 v[82:83], v[46:47], v[46:47]
	v_pk_mul_f32 v[84:85], v[48:49], v[48:49]
	v_pk_mul_f32 v[86:87], v[50:51], v[50:51]
	v_pk_mul_f32 v[88:89], v[52:53], v[52:53]
	v_pk_mul_f32 v[90:91], v[54:55], v[54:55]
	v_pk_mul_f32 v[92:93], v[56:57], v[56:57]
	v_add_f32_e32 v94, v82, v83
	v_add_f32_e32 v95, v84, v85
	v_add_f32_e32 v96, v86, v87
	v_add_f32_e32 v97, v88, v89
	v_add_f32_e32 v98, v90, v91
	v_add_f32_e32 v99, v92, v93
	ds_bpermute_b32 v100, v18, v94
	ds_bpermute_b32 v101, v18, v95
	ds_bpermute_b32 v102, v18, v96
	ds_bpermute_b32 v103, v18, v97
	ds_bpermute_b32 v104, v18, v98
	ds_bpermute_b32 v105, v18, v99
	v_mul_f32_e32 v70, 0xbfb8aa3b, v58
	v_mul_f32_e32 v71, 0xbfb8aa3b, v59
	v_mul_f32_e32 v72, 0xbfb8aa3b, v60
	v_mul_f32_e32 v73, 0xbfb8aa3b, v61
	v_mul_f32_e32 v74, 0xbfb8aa3b, v62
	v_mul_f32_e32 v75, 0xbfb8aa3b, v63
	v_mul_f32_e32 v76, 0xbfb8aa3b, v64
	v_mul_f32_e32 v77, 0xbfb8aa3b, v65
	v_mul_f32_e32 v78, 0xbfb8aa3b, v66
	v_mul_f32_e32 v79, 0xbfb8aa3b, v67
	v_mul_f32_e32 v80, 0xbfb8aa3b, v68
	v_mul_f32_e32 v81, 0xbfb8aa3b, v69
	s_waitcnt lgkmcnt(0)
	v_pk_add_f32 v[94:95], v[94:95], v[100:101]
	v_pk_add_f32 v[96:97], v[96:97], v[102:103]
	v_pk_add_f32 v[98:99], v[98:99], v[104:105]
	ds_bpermute_b32 v100, v19, v94
	ds_bpermute_b32 v101, v19, v95
	ds_bpermute_b32 v102, v19, v96
	ds_bpermute_b32 v103, v19, v97
	ds_bpermute_b32 v104, v19, v98
	ds_bpermute_b32 v105, v19, v99
	v_exp_f32_e32 v70, v70
	v_exp_f32_e32 v71, v71
	v_exp_f32_e32 v72, v72
	v_exp_f32_e32 v73, v73
	v_exp_f32_e32 v74, v74
	v_exp_f32_e32 v75, v75
	v_exp_f32_e32 v76, v76
	v_exp_f32_e32 v77, v77
	v_exp_f32_e32 v78, v78
	v_exp_f32_e32 v79, v79
	v_exp_f32_e32 v80, v80
	v_exp_f32_e32 v81, v81
	s_waitcnt lgkmcnt(0)
	v_pk_add_f32 v[94:95], v[94:95], v[100:101]
	v_pk_add_f32 v[96:97], v[96:97], v[102:103]
	v_pk_add_f32 v[98:99], v[98:99], v[104:105]
	ds_bpermute_b32 v100, v20, v94
	ds_bpermute_b32 v101, v20, v95
	ds_bpermute_b32 v102, v20, v96
	ds_bpermute_b32 v103, v20, v97
	ds_bpermute_b32 v104, v20, v98
	ds_bpermute_b32 v105, v20, v99
	v_add_f32_e32 v70, 1.0, v70
	v_add_f32_e32 v71, 1.0, v71
	v_add_f32_e32 v72, 1.0, v72
	v_add_f32_e32 v73, 1.0, v73
	v_add_f32_e32 v74, 1.0, v74
	v_add_f32_e32 v75, 1.0, v75
	v_add_f32_e32 v76, 1.0, v76
	v_add_f32_e32 v77, 1.0, v77
	v_add_f32_e32 v78, 1.0, v78
	v_add_f32_e32 v79, 1.0, v79
	v_add_f32_e32 v80, 1.0, v80
	v_add_f32_e32 v81, 1.0, v81
	s_waitcnt lgkmcnt(0)
	v_pk_add_f32 v[94:95], v[94:95], v[100:101]
	v_pk_add_f32 v[96:97], v[96:97], v[102:103]
	v_pk_add_f32 v[98:99], v[98:99], v[104:105]
	ds_bpermute_b32 v100, v21, v94
	ds_bpermute_b32 v101, v21, v95
	ds_bpermute_b32 v102, v21, v96
	ds_bpermute_b32 v103, v21, v97
	ds_bpermute_b32 v104, v21, v98
	ds_bpermute_b32 v105, v21, v99
	v_rcp_f32_e32 v70, v70
	v_rcp_f32_e32 v71, v71
	v_rcp_f32_e32 v72, v72
	v_rcp_f32_e32 v73, v73
	v_rcp_f32_e32 v74, v74
	v_rcp_f32_e32 v75, v75
	v_rcp_f32_e32 v76, v76
	v_rcp_f32_e32 v77, v77
	v_rcp_f32_e32 v78, v78
	v_rcp_f32_e32 v79, v79
	v_rcp_f32_e32 v80, v80
	v_rcp_f32_e32 v81, v81
	s_waitcnt lgkmcnt(0)
	v_pk_add_f32 v[94:95], v[94:95], v[100:101]
	v_pk_add_f32 v[96:97], v[96:97], v[102:103]
	v_pk_add_f32 v[98:99], v[98:99], v[104:105]
	ds_bpermute_b32 v100, v22, v94
	ds_bpermute_b32 v101, v22, v95
	ds_bpermute_b32 v102, v22, v96
	ds_bpermute_b32 v103, v22, v97
	ds_bpermute_b32 v104, v22, v98
	ds_bpermute_b32 v105, v22, v99
	v_pk_mul_f32 v[58:59], v[70:71], v[58:59]
	v_pk_mul_f32 v[60:61], v[72:73], v[60:61]
	v_pk_mul_f32 v[62:63], v[74:75], v[62:63]
	v_pk_mul_f32 v[64:65], v[76:77], v[64:65]
	v_pk_mul_f32 v[66:67], v[78:79], v[66:67]
	v_pk_mul_f32 v[68:69], v[80:81], v[68:69]
	v_mov_b32_e32 v106, 0x358637bd
	s_waitcnt lgkmcnt(0)
	v_pk_add_f32 v[94:95], v[94:95], v[100:101]
	v_pk_add_f32 v[96:97], v[96:97], v[102:103]
	v_pk_add_f32 v[98:99], v[98:99], v[104:105]
	ds_bpermute_b32 v100, v23, v94
	ds_bpermute_b32 v101, v23, v95
	ds_bpermute_b32 v102, v23, v96
	ds_bpermute_b32 v103, v23, v97
	ds_bpermute_b32 v104, v23, v98
	ds_bpermute_b32 v105, v23, v99
	s_waitcnt lgkmcnt(0)
	v_pk_add_f32 v[94:95], v[94:95], v[100:101]
	v_pk_add_f32 v[96:97], v[96:97], v[102:103]
	v_pk_add_f32 v[98:99], v[98:99], v[104:105]
	s_nop 0
	v_fma_f32 v94, v94, s8, v106
	v_fma_f32 v95, v95, s8, v106
	v_fma_f32 v96, v96, s8, v106
	v_fma_f32 v97, v97, s8, v106
	v_fma_f32 v98, v98, s8, v106
	v_fma_f32 v99, v99, s8, v106
	v_mul_f32_e32 v108, 0x4b800000, v94
	v_mul_f32_e32 v109, 0x4b800000, v95
	v_cmp_gt_f32_e32 vcc, s26, v94
	v_cmp_gt_f32_e64 s[0:1], s26, v95
	s_nop 0
	v_cndmask_b32_e32 v94, v94, v108, vcc
	v_cndmask_b32_e64 v95, v95, v109, s[0:1]
	v_rsq_f32_e32 v94, v94
	v_rsq_f32_e32 v95, v95
	v_mul_f32_e32 v108, 0x45800000, v94
	v_mul_f32_e32 v109, 0x45800000, v95
	v_cndmask_b32_e32 v114, v94, v108, vcc
	v_cndmask_b32_e64 v116, v95, v109, s[0:1]
	v_mul_f32_e32 v110, 0x4b800000, v96
	v_mul_f32_e32 v111, 0x4b800000, v97
	v_cmp_gt_f32_e32 vcc, s26, v96
	v_cmp_gt_f32_e64 s[0:1], s26, v97
	s_nop 0
	v_cndmask_b32_e32 v96, v96, v110, vcc
	v_cndmask_b32_e64 v97, v97, v111, s[0:1]
	v_rsq_f32_e32 v96, v96
	v_rsq_f32_e32 v97, v97
	v_mul_f32_e32 v110, 0x45800000, v96
	v_mul_f32_e32 v111, 0x45800000, v97
	v_cndmask_b32_e32 v118, v96, v110, vcc
	v_cndmask_b32_e64 v120, v97, v111, s[0:1]
	v_mul_f32_e32 v112, 0x4b800000, v98
	v_mul_f32_e32 v113, 0x4b800000, v99
	v_cmp_gt_f32_e32 vcc, s26, v98
	v_cmp_gt_f32_e64 s[0:1], s26, v99
	s_nop 0
	v_cndmask_b32_e32 v98, v98, v112, vcc
	v_cndmask_b32_e64 v99, v99, v113, s[0:1]
	v_rsq_f32_e32 v98, v98
	v_rsq_f32_e32 v99, v99
	v_mul_f32_e32 v112, 0x45800000, v98
	v_mul_f32_e32 v113, 0x45800000, v99
	v_cndmask_b32_e32 v122, v98, v112, vcc
	v_cndmask_b32_e64 v124, v99, v113, s[0:1]
	v_pk_mul_f32 v[46:47], v[114:115], v[46:47] op_sel_hi:[0,1]
	v_pk_mul_f32 v[48:49], v[116:117], v[48:49] op_sel_hi:[0,1]
	v_pk_mul_f32 v[50:51], v[118:119], v[50:51] op_sel_hi:[0,1]
	v_pk_mul_f32 v[52:53], v[120:121], v[52:53] op_sel_hi:[0,1]
	v_pk_mul_f32 v[54:55], v[122:123], v[54:55] op_sel_hi:[0,1]
	v_pk_mul_f32 v[56:57], v[124:125], v[56:57] op_sel_hi:[0,1]
	v_pk_mul_f32 v[46:47], v[0:1], v[46:47]
	v_pk_mul_f32 v[48:49], v[0:1], v[48:49]
	v_pk_mul_f32 v[50:51], v[0:1], v[50:51]
	v_pk_mul_f32 v[52:53], v[0:1], v[52:53]
	v_pk_mul_f32 v[54:55], v[0:1], v[54:55]
	v_pk_mul_f32 v[56:57], v[0:1], v[56:57]
	v_pk_mul_f32 v[46:47], v[58:59], v[46:47]
	v_pk_mul_f32 v[48:49], v[60:61], v[48:49]
	v_pk_mul_f32 v[50:51], v[62:63], v[50:51]
	v_pk_mul_f32 v[52:53], v[64:65], v[52:53]
	v_pk_mul_f32 v[54:55], v[66:67], v[54:55]
	v_pk_mul_f32 v[56:57], v[68:69], v[56:57]
	v_cvt_pk_bf16_f32 v108, v46, v47
	v_cvt_pk_bf16_f32 v109, v48, v49
	v_cvt_pk_bf16_f32 v110, v50, v51
	v_cvt_pk_bf16_f32 v111, v52, v53
	v_cvt_pk_bf16_f32 v112, v54, v55
	v_cvt_pk_bf16_f32 v113, v56, v57
	global_store_dword v[4:5], v108, off
	global_store_dword v[4:5], v109, off offset:256
	global_store_dword v[4:5], v110, off offset:512
	global_store_dword v[4:5], v111, off offset:768
	global_store_dword v[4:5], v112, off offset:1024
	global_store_dword v[4:5], v113, off offset:1280
	s_branch .LBB0_1907
